# adds cheaper per-token output reduction in the RWKV pass-1 loop and spreads the diagonal combine over twice as many workgroups
# speedup vs baseline: 1.0047x; 1.0047x over previous
; #define LAS __attribute__((address_space(3)))
; template <int pass>
; __device__ __forceinline__ void rw_item(const Params& p, int l, int seg, int h, LAS float* sm, int tid, int lane, int wave) {
;     ...
;             const f32x4 w4 = nw4, k4 = nk4, a4 = na4, b4 = nb4, q4 = nq4; const f32x2 vv = nvv;
;             {
;                 const int tn = (t + 1 < TS) ? t + 1 : t, on = tn * 64 + kq * 4;
;                 nw4 = *(const LAS f32x4*)(bf + 1024 + on); nk4 = *(const LAS f32x4*)(bf + 2048 + on);
;                 na4 = *(const LAS f32x4*)(bf + 3072 + on); nb4 = *(const LAS f32x4*)(bf + 4096 + on);
;                 nvv = *(const LAS f32x2*)(bf + 5120 + tn * 64 + j0);
;                 if (pass == 1) nq4 = *(const LAS f32x4*)(bf + on);
;             }
;             const f32x2 vA = {vv.x, vv.x}, vB = {vv.y, vv.y};
;             f32x2 ua = b4.xy * sA[0], ub = b4.xy * sB[0];
;             ua = b4.zw * sA[1] + ua; ub = b4.zw * sB[1] + ub;
;             float uA = ua.x + ua.y, uB = ub.x + ub.y, gA = 0.f, gB = 0.f;
;             if (pass == 0) {
;                 f32x2 qa = b4.xy * pA[0], qb = b4.xy * pB[0];
;                 qa = b4.zw * pA[1] + qa; qb = b4.zw * pB[1] + qb;
;                 gA = qa.x + qa.y; gB = qb.x + qb.y;
;                 kq_sum16x4(uA, uB, gA, gB);
;             } else { uA = kq_sum<16>(uA); uB = kq_sum<16>(uB); }
;             const f32x2 uA2 = {uA, uA}, uB2 = {uB, uB};
;             { const f32x2 t0_ = k4.xy * vA - a4.xy * uA2, t1_ = k4.zw * vA - a4.zw * uA2; sA[0] = w4.xy * sA[0] + t0_; sA[1] = w4.zw * sA[1] + t1_; }
;             { const f32x2 t0_ = k4.xy * vB - a4.xy * uB2, t1_ = k4.zw * vB - a4.zw * uB2; sB[0] = w4.xy * sB[0] + t0_; sB[1] = w4.zw * sB[1] + t1_; }
;             if (pass == 0) {
;                 const f32x2 gA2 = {gA, gA}, gB2 = {gB, gB};
;                 pA[0] = w4.xy * pA[0] - a4.xy * gA2; pA[1] = w4.zw * pA[1] - a4.zw * gA2;
;                 pB[0] = w4.xy * pB[0] - a4.xy * gB2; pB[1] = w4.zw * pB[1] - a4.zw * gB2;
;             } else {
;                 f32x2 oa = q4.xy * sA[0], ob2 = q4.xy * sB[0];
;                 oa = q4.zw * sA[1] + oa; ob2 = q4.zw * sB[1] + ob2;
;                 const float oA = kq_sum<16>(oa.x + oa.y), oB = kq_sum<16>(ob2.x + ob2.y);
;                 if (kq == 0) *(LAS f32x2*)(ob + t * 64 + j0) = (f32x2){oA, oB};
.LBB0_457:
	s_waitcnt lgkmcnt(2)
	v_pk_mul_f32 v[52:53], v[28:29], v[8:9]
	v_pk_mul_f32 v[28:29], v[28:29], v[4:5]
	v_pk_fma_f32 v[52:53], v[26:27], v[6:7], v[52:53]
	v_pk_fma_f32 v[26:27], v[26:27], v[2:3], v[28:29]
	v_add_f32_e32 v28, v52, v53
	v_add_f32_e32 v27, v26, v27
	v_add_u32_e32 v97, s38, v94
	v_add_f32_dpp v26, v28, v28 quad_perm:[1,0,3,2] row_mask:0xf bank_mask:0xf bound_ctrl:1
	v_add_f32_dpp v27, v27, v27 quad_perm:[1,0,3,2] row_mask:0xf bank_mask:0xf bound_ctrl:1
	ds_read_b128 v[34:37], v97 offset:8192
	ds_read_b128 v[38:41], v97 offset:12288
	v_add_f32_dpp v26, v26, v26 quad_perm:[2,3,0,1] row_mask:0xf bank_mask:0xf bound_ctrl:1
	v_add_f32_dpp v27, v27, v27 quad_perm:[2,3,0,1] row_mask:0xf bank_mask:0xf bound_ctrl:1
	v_add_u32_e32 v98, s38, v92
	v_add_f32_dpp v26, v26, v26 row_half_mirror row_mask:0xf bank_mask:0xf bound_ctrl:1
	v_add_f32_dpp v27, v27, v27 row_half_mirror row_mask:0xf bank_mask:0xf bound_ctrl:1
	ds_read_b128 v[46:49], v97 offset:16384
	ds_read_b64 v[66:67], v98
	ds_read_b128 v[42:45], v97 offset:4096
	ds_read_b128 v[30:33], v97
	v_add_f32_dpp v26, v26, v26 row_mirror row_mask:0xf bank_mask:0xf bound_ctrl:1
	v_add_f32_dpp v28, v27, v27 row_mirror row_mask:0xf bank_mask:0xf bound_ctrl:1
	v_pk_mul_f32 v[52:53], v[18:19], v[26:27] op_sel_hi:[1,0]
	v_pk_mul_f32 v[18:19], v[18:19], v[28:29] op_sel_hi:[1,0]
	s_waitcnt lgkmcnt(7)
	v_pk_fma_f32 v[52:53], v[14:15], v[50:51], v[52:53] op_sel_hi:[1,0,1] neg_lo:[0,0,1] neg_hi:[0,0,1]
	v_pk_mul_f32 v[26:27], v[20:21], v[26:27] op_sel_hi:[1,0]
	v_pk_fma_f32 v[14:15], v[14:15], v[50:51], v[18:19] op_sel:[0,1,0] neg_lo:[0,0,1] neg_hi:[0,0,1]
	v_pk_mul_f32 v[18:19], v[20:21], v[28:29] op_sel_hi:[1,0]
	v_pk_fma_f32 v[26:27], v[16:17], v[50:51], v[26:27] op_sel_hi:[1,0,1] neg_lo:[0,0,1] neg_hi:[0,0,1]
	v_pk_fma_f32 v[6:7], v[10:11], v[6:7], v[52:53]
	v_pk_fma_f32 v[16:17], v[16:17], v[50:51], v[18:19] op_sel:[0,1,0] neg_lo:[0,0,1] neg_hi:[0,0,1]
	v_pk_fma_f32 v[14:15], v[10:11], v[2:3], v[14:15]
	v_pk_fma_f32 v[8:9], v[12:13], v[8:9], v[26:27]
	v_pk_fma_f32 v[16:17], v[12:13], v[4:5], v[16:17]
	s_waitcnt lgkmcnt(6)
	v_pk_mul_f32 v[2:3], v[22:23], v[6:7]
	v_pk_mul_f32 v[4:5], v[22:23], v[14:15]
	v_pk_fma_f32 v[2:3], v[24:25], v[8:9], v[2:3]
	v_pk_fma_f32 v[4:5], v[24:25], v[16:17], v[4:5]
	v_add_f32_e32 v2, v2, v3
	v_add_f32_e32 v3, v4, v5
	v_add_u32_e32 v96, s38, v95
	s_nop 0
	v_add_f32_dpp v2, v2, v2 quad_perm:[1,0,3,2] row_mask:0xf bank_mask:0xf bound_ctrl:1
	v_add_f32_dpp v3, v3, v3 quad_perm:[1,0,3,2] row_mask:0xf bank_mask:0xf bound_ctrl:1
	s_nop 0
	v_add_f32_dpp v2, v2, v2 quad_perm:[2,3,0,1] row_mask:0xf bank_mask:0xf bound_ctrl:1
	v_add_f32_dpp v3, v3, v3 quad_perm:[2,3,0,1] row_mask:0xf bank_mask:0xf bound_ctrl:1
	s_nop 0
	v_add_f32_dpp v2, v2, v2 row_half_mirror row_mask:0xf bank_mask:0xf bound_ctrl:1
	v_add_f32_dpp v3, v3, v3 row_half_mirror row_mask:0xf bank_mask:0xf bound_ctrl:1
	s_nop 0
	v_add_f32_dpp v2, v2, v2 row_mirror row_mask:0xf bank_mask:0xf bound_ctrl:1
	v_add_f32_dpp v3, v3, v3 row_mirror row_mask:0xf bank_mask:0xf bound_ctrl:1
	s_and_saveexec_b64 s[0:1], vcc
	ds_write_b64 v96, v[2:3]
	s_or_b64 exec, exec, s[0:1]
	s_waitcnt lgkmcnt(3)
	v_pk_mul_f32 v[26:27], v[48:49], v[8:9]
	v_pk_mul_f32 v[28:29], v[48:49], v[16:17]
	v_pk_fma_f32 v[26:27], v[46:47], v[6:7], v[26:27]
	v_pk_fma_f32 v[28:29], v[46:47], v[14:15], v[28:29]
	v_add_f32_e32 v26, v26, v27
	v_add_f32_e32 v27, v28, v29
	ds_read_b128 v[10:13], v97 offset:8448
	ds_read_b128 v[22:25], v97 offset:12544
	ds_read_b128 v[50:53], v97 offset:16640
	ds_read_b64 v[68:69], v98 offset:256
	ds_read_b128 v[18:21], v97 offset:4352
	ds_read_b128 v[2:5], v97 offset:256
	v_add_f32_dpp v26, v26, v26 quad_perm:[1,0,3,2] row_mask:0xf bank_mask:0xf bound_ctrl:1
	v_add_f32_dpp v27, v27, v27 quad_perm:[1,0,3,2] row_mask:0xf bank_mask:0xf bound_ctrl:1
	s_nop 0
	v_add_f32_dpp v26, v26, v26 quad_perm:[2,3,0,1] row_mask:0xf bank_mask:0xf bound_ctrl:1
	v_add_f32_dpp v27, v27, v27 quad_perm:[2,3,0,1] row_mask:0xf bank_mask:0xf bound_ctrl:1
	s_nop 0
	v_add_f32_dpp v26, v26, v26 row_half_mirror row_mask:0xf bank_mask:0xf bound_ctrl:1
	v_add_f32_dpp v27, v27, v27 row_half_mirror row_mask:0xf bank_mask:0xf bound_ctrl:1
	s_nop 0
	v_add_f32_dpp v26, v26, v26 row_mirror row_mask:0xf bank_mask:0xf bound_ctrl:1
	v_pk_mul_f32 v[46:47], v[38:39], v[26:27] op_sel_hi:[1,0]
	v_add_f32_dpp v28, v27, v27 row_mirror row_mask:0xf bank_mask:0xf bound_ctrl:1
	s_waitcnt lgkmcnt(8)
	v_pk_fma_f32 v[46:47], v[34:35], v[66:67], v[46:47] op_sel_hi:[1,0,1] neg_lo:[0,0,1] neg_hi:[0,0,1]
	v_pk_mul_f32 v[26:27], v[40:41], v[26:27] op_sel_hi:[1,0]
	s_waitcnt lgkmcnt(7)
	v_pk_fma_f32 v[46:47], v[42:43], v[6:7], v[46:47]
	v_pk_fma_f32 v[26:27], v[36:37], v[66:67], v[26:27] op_sel_hi:[1,0,1] neg_lo:[0,0,1] neg_hi:[0,0,1]
	v_pk_mul_f32 v[6:7], v[38:39], v[28:29] op_sel_hi:[1,0]
	v_pk_fma_f32 v[48:49], v[44:45], v[8:9], v[26:27]
	v_pk_fma_f32 v[6:7], v[34:35], v[66:67], v[6:7] op_sel:[0,1,0] neg_lo:[0,0,1] neg_hi:[0,0,1]
	v_pk_mul_f32 v[8:9], v[40:41], v[28:29] op_sel_hi:[1,0]
	v_pk_fma_f32 v[38:39], v[42:43], v[14:15], v[6:7]
	v_pk_fma_f32 v[8:9], v[36:37], v[66:67], v[8:9] op_sel:[0,1,0] neg_lo:[0,0,1] neg_hi:[0,0,1]
	s_waitcnt lgkmcnt(6)
; #define LAS __attribute__((address_space(3)))
; template <int pass>
; __device__ __forceinline__ void rw_item(const Params& p, int l, int seg, int h, LAS float* sm, int tid, int lane, int wave) {
;     ...
;             const f32x4 w4 = nw4, k4 = nk4, a4 = na4, b4 = nb4, q4 = nq4; const f32x2 vv = nvv;
;             {
;                 const int tn = (t + 1 < TS) ? t + 1 : t, on = tn * 64 + kq * 4;
;                 nw4 = *(const LAS f32x4*)(bf + 1024 + on); nk4 = *(const LAS f32x4*)(bf + 2048 + on);
;                 na4 = *(const LAS f32x4*)(bf + 3072 + on); nb4 = *(const LAS f32x4*)(bf + 4096 + on);
;                 nvv = *(const LAS f32x2*)(bf + 5120 + tn * 64 + j0);
;                 if (pass == 1) nq4 = *(const LAS f32x4*)(bf + on);
;             }
;             const f32x2 vA = {vv.x, vv.x}, vB = {vv.y, vv.y};
;             f32x2 ua = b4.xy * sA[0], ub = b4.xy * sB[0];
;             ua = b4.zw * sA[1] + ua; ub = b4.zw * sB[1] + ub;
;             float uA = ua.x + ua.y, uB = ub.x + ub.y, gA = 0.f, gB = 0.f;
;             if (pass == 0) {
;                 f32x2 qa = b4.xy * pA[0], qb = b4.xy * pB[0];
;                 qa = b4.zw * pA[1] + qa; qb = b4.zw * pB[1] + qb;
;                 gA = qa.x + qa.y; gB = qb.x + qb.y;
;                 kq_sum16x4(uA, uB, gA, gB);
;             } else { uA = kq_sum<16>(uA); uB = kq_sum<16>(uB); }
;             const f32x2 uA2 = {uA, uA}, uB2 = {uB, uB};
;             { const f32x2 t0_ = k4.xy * vA - a4.xy * uA2, t1_ = k4.zw * vA - a4.zw * uA2; sA[0] = w4.xy * sA[0] + t0_; sA[1] = w4.zw * sA[1] + t1_; }
;             { const f32x2 t0_ = k4.xy * vB - a4.xy * uB2, t1_ = k4.zw * vB - a4.zw * uB2; sB[0] = w4.xy * sB[0] + t0_; sB[1] = w4.zw * sB[1] + t1_; }
;             if (pass == 0) {
;                 const f32x2 gA2 = {gA, gA}, gB2 = {gB, gB};
;                 pA[0] = w4.xy * pA[0] - a4.xy * gA2; pA[1] = w4.zw * pA[1] - a4.zw * gA2;
;                 pB[0] = w4.xy * pB[0] - a4.xy * gB2; pB[1] = w4.zw * pB[1] - a4.zw * gB2;
;             } else {
;                 f32x2 oa = q4.xy * sA[0], ob2 = q4.xy * sB[0];
;                 oa = q4.zw * sA[1] + oa; ob2 = q4.zw * sB[1] + ob2;
;                 const float oA = kq_sum<16>(oa.x + oa.y), oB = kq_sum<16>(ob2.x + ob2.y);
;                 if (kq == 0) *(LAS f32x2*)(ob + t * 64 + j0) = (f32x2){oA, oB};
	v_pk_mul_f32 v[6:7], v[30:31], v[46:47]
	v_pk_fma_f32 v[40:41], v[44:45], v[16:17], v[8:9]
	v_pk_mul_f32 v[8:9], v[30:31], v[38:39]
	v_pk_fma_f32 v[6:7], v[32:33], v[48:49], v[6:7]
	v_pk_fma_f32 v[8:9], v[32:33], v[40:41], v[8:9]
	v_add_f32_e32 v6, v6, v7
	v_add_f32_e32 v7, v8, v9
	s_nop 1
	v_add_f32_dpp v6, v6, v6 quad_perm:[1,0,3,2] row_mask:0xf bank_mask:0xf bound_ctrl:1
	v_add_f32_dpp v7, v7, v7 quad_perm:[1,0,3,2] row_mask:0xf bank_mask:0xf bound_ctrl:1
	s_nop 0
	v_add_f32_dpp v6, v6, v6 quad_perm:[2,3,0,1] row_mask:0xf bank_mask:0xf bound_ctrl:1
	v_add_f32_dpp v7, v7, v7 quad_perm:[2,3,0,1] row_mask:0xf bank_mask:0xf bound_ctrl:1
	s_nop 0
	v_add_f32_dpp v6, v6, v6 row_half_mirror row_mask:0xf bank_mask:0xf bound_ctrl:1
	v_add_f32_dpp v7, v7, v7 row_half_mirror row_mask:0xf bank_mask:0xf bound_ctrl:1
	s_nop 0
	v_add_f32_dpp v6, v6, v6 row_mirror row_mask:0xf bank_mask:0xf bound_ctrl:1
	v_add_f32_dpp v7, v7, v7 row_mirror row_mask:0xf bank_mask:0xf bound_ctrl:1
	s_and_saveexec_b64 s[0:1], vcc
	ds_write_b64 v96, v[6:7] offset:256
	s_or_b64 exec, exec, s[0:1]
	s_waitcnt lgkmcnt(3)
	v_pk_mul_f32 v[44:45], v[52:53], v[48:49]
	v_pk_mul_f32 v[52:53], v[52:53], v[40:41]
	v_pk_fma_f32 v[44:45], v[50:51], v[46:47], v[44:45]
	v_pk_fma_f32 v[50:51], v[50:51], v[38:39], v[52:53]
	v_add_f32_e32 v44, v44, v45
	v_add_f32_e32 v45, v50, v51
	ds_read_b128 v[14:17], v97 offset:8704
	ds_read_b128 v[30:33], v97 offset:12800
	ds_read_b128 v[34:37], v97 offset:16896
	ds_read_b64 v[42:43], v98 offset:512
	ds_read_b128 v[26:29], v97 offset:4608
	ds_read_b128 v[6:9], v97 offset:512
	v_add_f32_dpp v44, v44, v44 quad_perm:[1,0,3,2] row_mask:0xf bank_mask:0xf bound_ctrl:1
	v_add_f32_dpp v45, v45, v45 quad_perm:[1,0,3,2] row_mask:0xf bank_mask:0xf bound_ctrl:1
	s_nop 0
	v_add_f32_dpp v44, v44, v44 quad_perm:[2,3,0,1] row_mask:0xf bank_mask:0xf bound_ctrl:1
	v_add_f32_dpp v45, v45, v45 quad_perm:[2,3,0,1] row_mask:0xf bank_mask:0xf bound_ctrl:1
	s_nop 0
	v_add_f32_dpp v44, v44, v44 row_half_mirror row_mask:0xf bank_mask:0xf bound_ctrl:1
	v_add_f32_dpp v45, v45, v45 row_half_mirror row_mask:0xf bank_mask:0xf bound_ctrl:1
	s_nop 0
	v_add_f32_dpp v44, v44, v44 row_mirror row_mask:0xf bank_mask:0xf bound_ctrl:1
	v_add_f32_dpp v50, v45, v45 row_mirror row_mask:0xf bank_mask:0xf bound_ctrl:1
	v_pk_mul_f32 v[52:53], v[22:23], v[44:45] op_sel_hi:[1,0]
	v_pk_mul_f32 v[22:23], v[22:23], v[50:51] op_sel_hi:[1,0]
	s_waitcnt lgkmcnt(8)
	v_pk_fma_f32 v[52:53], v[10:11], v[68:69], v[52:53] op_sel_hi:[1,0,1] neg_lo:[0,0,1] neg_hi:[0,0,1]
	v_pk_mul_f32 v[44:45], v[24:25], v[44:45] op_sel_hi:[1,0]
	v_pk_fma_f32 v[10:11], v[10:11], v[68:69], v[22:23] op_sel:[0,1,0] neg_lo:[0,0,1] neg_hi:[0,0,1]
	v_pk_mul_f32 v[22:23], v[24:25], v[50:51] op_sel_hi:[1,0]
	v_pk_fma_f32 v[44:45], v[12:13], v[68:69], v[44:45] op_sel_hi:[1,0,1] neg_lo:[0,0,1] neg_hi:[0,0,1]
	s_waitcnt lgkmcnt(7)
	v_pk_fma_f32 v[46:47], v[18:19], v[46:47], v[52:53]
	v_pk_fma_f32 v[12:13], v[12:13], v[68:69], v[22:23] op_sel:[0,1,0] neg_lo:[0,0,1] neg_hi:[0,0,1]
	v_pk_fma_f32 v[50:51], v[18:19], v[38:39], v[10:11]
	v_pk_fma_f32 v[48:49], v[20:21], v[48:49], v[44:45]
	v_pk_fma_f32 v[52:53], v[20:21], v[40:41], v[12:13]
	s_waitcnt lgkmcnt(6)
	v_pk_mul_f32 v[10:11], v[2:3], v[46:47]
	v_pk_mul_f32 v[2:3], v[2:3], v[50:51]
	v_pk_fma_f32 v[10:11], v[4:5], v[48:49], v[10:11]
	v_pk_fma_f32 v[2:3], v[4:5], v[52:53], v[2:3]
	v_add_f32_e32 v3, v2, v3
	v_add_f32_e32 v2, v10, v11
	s_nop 1
	v_add_f32_dpp v2, v2, v2 quad_perm:[1,0,3,2] row_mask:0xf bank_mask:0xf bound_ctrl:1
	v_add_f32_dpp v3, v3, v3 quad_perm:[1,0,3,2] row_mask:0xf bank_mask:0xf bound_ctrl:1
	s_nop 0
	v_add_f32_dpp v2, v2, v2 quad_perm:[2,3,0,1] row_mask:0xf bank_mask:0xf bound_ctrl:1
	v_add_f32_dpp v3, v3, v3 quad_perm:[2,3,0,1] row_mask:0xf bank_mask:0xf bound_ctrl:1
	s_nop 0
	v_add_f32_dpp v2, v2, v2 row_half_mirror row_mask:0xf bank_mask:0xf bound_ctrl:1
	v_add_f32_dpp v3, v3, v3 row_half_mirror row_mask:0xf bank_mask:0xf bound_ctrl:1
	s_nop 0
	v_add_f32_dpp v2, v2, v2 row_mirror row_mask:0xf bank_mask:0xf bound_ctrl:1
	v_add_f32_dpp v3, v3, v3 row_mirror row_mask:0xf bank_mask:0xf bound_ctrl:1
	s_and_saveexec_b64 s[0:1], vcc
	ds_write_b64 v96, v[2:3] offset:512
	s_or_b64 exec, exec, s[0:1]
	s_waitcnt lgkmcnt(3)
	v_pk_mul_f32 v[66:67], v[36:37], v[48:49]
	v_pk_mul_f32 v[36:37], v[36:37], v[52:53]
	v_pk_fma_f32 v[66:67], v[34:35], v[46:47], v[66:67]
	v_pk_fma_f32 v[34:35], v[34:35], v[50:51], v[36:37]
	v_add_f32_e32 v36, v66, v67
	v_add_f32_e32 v35, v34, v35
	ds_read_b128 v[10:13], v97 offset:8960
	ds_read_b128 v[22:25], v97 offset:13056
	ds_read_b128 v[38:41], v97 offset:17152
	ds_read_b64 v[44:45], v98 offset:768
	ds_read_b128 v[18:21], v97 offset:4864
	ds_read_b128 v[2:5], v97 offset:768
	v_add_f32_dpp v34, v36, v36 quad_perm:[1,0,3,2] row_mask:0xf bank_mask:0xf bound_ctrl:1
	v_add_f32_dpp v35, v35, v35 quad_perm:[1,0,3,2] row_mask:0xf bank_mask:0xf bound_ctrl:1
	s_nop 0
	v_add_f32_dpp v34, v34, v34 quad_perm:[2,3,0,1] row_mask:0xf bank_mask:0xf bound_ctrl:1
	v_add_f32_dpp v35, v35, v35 quad_perm:[2,3,0,1] row_mask:0xf bank_mask:0xf bound_ctrl:1
	s_nop 0
	v_add_f32_dpp v34, v34, v34 row_half_mirror row_mask:0xf bank_mask:0xf bound_ctrl:1
	v_add_f32_dpp v35, v35, v35 row_half_mirror row_mask:0xf bank_mask:0xf bound_ctrl:1
	s_nop 0
	v_add_f32_dpp v34, v34, v34 row_mirror row_mask:0xf bank_mask:0xf bound_ctrl:1
	v_add_f32_dpp v36, v35, v35 row_mirror row_mask:0xf bank_mask:0xf bound_ctrl:1
	v_pk_mul_f32 v[66:67], v[30:31], v[34:35] op_sel_hi:[1,0]
	v_pk_mul_f32 v[30:31], v[30:31], v[36:37] op_sel_hi:[1,0]
	s_waitcnt lgkmcnt(8)
; #define LAS __attribute__((address_space(3)))
; template <int pass>
; __device__ __forceinline__ void rw_item(const Params& p, int l, int seg, int h, LAS float* sm, int tid, int lane, int wave) {
;     ...
;             const f32x4 w4 = nw4, k4 = nk4, a4 = na4, b4 = nb4, q4 = nq4; const f32x2 vv = nvv;
;             {
;                 const int tn = (t + 1 < TS) ? t + 1 : t, on = tn * 64 + kq * 4;
;                 nw4 = *(const LAS f32x4*)(bf + 1024 + on); nk4 = *(const LAS f32x4*)(bf + 2048 + on);
;                 na4 = *(const LAS f32x4*)(bf + 3072 + on); nb4 = *(const LAS f32x4*)(bf + 4096 + on);
;                 nvv = *(const LAS f32x2*)(bf + 5120 + tn * 64 + j0);
;                 if (pass == 1) nq4 = *(const LAS f32x4*)(bf + on);
;             }
;             const f32x2 vA = {vv.x, vv.x}, vB = {vv.y, vv.y};
;             f32x2 ua = b4.xy * sA[0], ub = b4.xy * sB[0];
;             ua = b4.zw * sA[1] + ua; ub = b4.zw * sB[1] + ub;
;             float uA = ua.x + ua.y, uB = ub.x + ub.y, gA = 0.f, gB = 0.f;
;             if (pass == 0) {
;                 f32x2 qa = b4.xy * pA[0], qb = b4.xy * pB[0];
;                 qa = b4.zw * pA[1] + qa; qb = b4.zw * pB[1] + qb;
;                 gA = qa.x + qa.y; gB = qb.x + qb.y;
;                 kq_sum16x4(uA, uB, gA, gB);
;             } else { uA = kq_sum<16>(uA); uB = kq_sum<16>(uB); }
;             const f32x2 uA2 = {uA, uA}, uB2 = {uB, uB};
;             { const f32x2 t0_ = k4.xy * vA - a4.xy * uA2, t1_ = k4.zw * vA - a4.zw * uA2; sA[0] = w4.xy * sA[0] + t0_; sA[1] = w4.zw * sA[1] + t1_; }
;             { const f32x2 t0_ = k4.xy * vB - a4.xy * uB2, t1_ = k4.zw * vB - a4.zw * uB2; sB[0] = w4.xy * sB[0] + t0_; sB[1] = w4.zw * sB[1] + t1_; }
;             if (pass == 0) {
;                 const f32x2 gA2 = {gA, gA}, gB2 = {gB, gB};
;                 pA[0] = w4.xy * pA[0] - a4.xy * gA2; pA[1] = w4.zw * pA[1] - a4.zw * gA2;
;                 pB[0] = w4.xy * pB[0] - a4.xy * gB2; pB[1] = w4.zw * pB[1] - a4.zw * gB2;
;             } else {
;                 f32x2 oa = q4.xy * sA[0], ob2 = q4.xy * sB[0];
;                 oa = q4.zw * sA[1] + oa; ob2 = q4.zw * sB[1] + ob2;
;                 const float oA = kq_sum<16>(oa.x + oa.y), oB = kq_sum<16>(ob2.x + ob2.y);
;                 if (kq == 0) *(LAS f32x2*)(ob + t * 64 + j0) = (f32x2){oA, oB};
	v_pk_fma_f32 v[66:67], v[14:15], v[42:43], v[66:67] op_sel_hi:[1,0,1] neg_lo:[0,0,1] neg_hi:[0,0,1]
	v_pk_mul_f32 v[34:35], v[32:33], v[34:35] op_sel_hi:[1,0]
	v_pk_fma_f32 v[14:15], v[14:15], v[42:43], v[30:31] op_sel:[0,1,0] neg_lo:[0,0,1] neg_hi:[0,0,1]
	v_pk_mul_f32 v[30:31], v[32:33], v[36:37] op_sel_hi:[1,0]
	v_pk_fma_f32 v[34:35], v[16:17], v[42:43], v[34:35] op_sel_hi:[1,0,1] neg_lo:[0,0,1] neg_hi:[0,0,1]
	s_waitcnt lgkmcnt(7)
	v_pk_fma_f32 v[46:47], v[26:27], v[46:47], v[66:67]
	v_pk_fma_f32 v[16:17], v[16:17], v[42:43], v[30:31] op_sel:[0,1,0] neg_lo:[0,0,1] neg_hi:[0,0,1]
	v_pk_fma_f32 v[42:43], v[26:27], v[50:51], v[14:15]
	v_pk_fma_f32 v[48:49], v[28:29], v[48:49], v[34:35]
	v_pk_fma_f32 v[52:53], v[28:29], v[52:53], v[16:17]
	s_waitcnt lgkmcnt(6)
	v_pk_mul_f32 v[14:15], v[6:7], v[46:47]
	v_pk_mul_f32 v[6:7], v[6:7], v[42:43]
	v_pk_fma_f32 v[14:15], v[8:9], v[48:49], v[14:15]
	v_pk_fma_f32 v[6:7], v[8:9], v[52:53], v[6:7]
	v_add_f32_e32 v7, v6, v7
	v_add_f32_e32 v6, v14, v15
	s_nop 1
	v_add_f32_dpp v6, v6, v6 quad_perm:[1,0,3,2] row_mask:0xf bank_mask:0xf bound_ctrl:1
	v_add_f32_dpp v7, v7, v7 quad_perm:[1,0,3,2] row_mask:0xf bank_mask:0xf bound_ctrl:1
	s_nop 0
	v_add_f32_dpp v6, v6, v6 quad_perm:[2,3,0,1] row_mask:0xf bank_mask:0xf bound_ctrl:1
	v_add_f32_dpp v7, v7, v7 quad_perm:[2,3,0,1] row_mask:0xf bank_mask:0xf bound_ctrl:1
	s_nop 0
	v_add_f32_dpp v6, v6, v6 row_half_mirror row_mask:0xf bank_mask:0xf bound_ctrl:1
	v_add_f32_dpp v7, v7, v7 row_half_mirror row_mask:0xf bank_mask:0xf bound_ctrl:1
	s_nop 0
	v_add_f32_dpp v6, v6, v6 row_mirror row_mask:0xf bank_mask:0xf bound_ctrl:1
	v_add_f32_dpp v7, v7, v7 row_mirror row_mask:0xf bank_mask:0xf bound_ctrl:1
	s_and_saveexec_b64 s[0:1], vcc
	ds_write_b64 v96, v[6:7] offset:768
	s_or_b64 exec, exec, s[0:1]
	s_waitcnt lgkmcnt(3)
	v_pk_mul_f32 v[66:67], v[40:41], v[48:49]
	v_pk_mul_f32 v[40:41], v[40:41], v[52:53]
	v_pk_fma_f32 v[66:67], v[38:39], v[46:47], v[66:67]
	v_pk_fma_f32 v[38:39], v[38:39], v[42:43], v[40:41]
	v_add_f32_e32 v40, v66, v67
	v_add_f32_e32 v39, v38, v39
	ds_read_b128 v[14:17], v97 offset:9216
	ds_read_b128 v[30:33], v97 offset:13312
	ds_read_b128 v[34:37], v97 offset:17408
	ds_read_b64 v[50:51], v98 offset:1024
	ds_read_b128 v[26:29], v97 offset:5120
	ds_read_b128 v[6:9], v97 offset:1024
	v_add_f32_dpp v38, v40, v40 quad_perm:[1,0,3,2] row_mask:0xf bank_mask:0xf bound_ctrl:1
	v_add_f32_dpp v39, v39, v39 quad_perm:[1,0,3,2] row_mask:0xf bank_mask:0xf bound_ctrl:1
	s_nop 0
	v_add_f32_dpp v38, v38, v38 quad_perm:[2,3,0,1] row_mask:0xf bank_mask:0xf bound_ctrl:1
	v_add_f32_dpp v39, v39, v39 quad_perm:[2,3,0,1] row_mask:0xf bank_mask:0xf bound_ctrl:1
	s_nop 0
	v_add_f32_dpp v38, v38, v38 row_half_mirror row_mask:0xf bank_mask:0xf bound_ctrl:1
	v_add_f32_dpp v39, v39, v39 row_half_mirror row_mask:0xf bank_mask:0xf bound_ctrl:1
	s_nop 0
	v_add_f32_dpp v38, v38, v38 row_mirror row_mask:0xf bank_mask:0xf bound_ctrl:1
	v_add_f32_dpp v66, v39, v39 row_mirror row_mask:0xf bank_mask:0xf bound_ctrl:1
	v_pk_mul_f32 v[40:41], v[22:23], v[38:39] op_sel_hi:[1,0]
	v_pk_mul_f32 v[38:39], v[24:25], v[38:39] op_sel_hi:[1,0]
	v_pk_mul_f32 v[22:23], v[22:23], v[66:67] op_sel_hi:[1,0]
	s_waitcnt lgkmcnt(8)
	v_pk_fma_f32 v[40:41], v[10:11], v[44:45], v[40:41] op_sel_hi:[1,0,1] neg_lo:[0,0,1] neg_hi:[0,0,1]
	v_pk_fma_f32 v[68:69], v[12:13], v[44:45], v[38:39] op_sel_hi:[1,0,1] neg_lo:[0,0,1] neg_hi:[0,0,1]
	v_pk_fma_f32 v[10:11], v[10:11], v[44:45], v[22:23] op_sel:[0,1,0] neg_lo:[0,0,1] neg_hi:[0,0,1]
	v_pk_mul_f32 v[22:23], v[24:25], v[66:67] op_sel_hi:[1,0]
	s_waitcnt lgkmcnt(7)
	v_pk_fma_f32 v[38:39], v[18:19], v[46:47], v[40:41]
	v_pk_fma_f32 v[40:41], v[20:21], v[48:49], v[68:69]
	v_pk_fma_f32 v[12:13], v[12:13], v[44:45], v[22:23] op_sel:[0,1,0] neg_lo:[0,0,1] neg_hi:[0,0,1]
	v_pk_fma_f32 v[68:69], v[18:19], v[42:43], v[10:11]
	v_pk_fma_f32 v[52:53], v[20:21], v[52:53], v[12:13]
	s_waitcnt lgkmcnt(6)
	v_pk_mul_f32 v[10:11], v[2:3], v[38:39]
	v_pk_mul_f32 v[2:3], v[2:3], v[68:69]
	v_pk_fma_f32 v[10:11], v[4:5], v[40:41], v[10:11]
	v_pk_fma_f32 v[2:3], v[4:5], v[52:53], v[2:3]
	v_add_f32_e32 v3, v2, v3
	v_add_f32_e32 v2, v10, v11
	s_nop 1
	v_add_f32_dpp v2, v2, v2 quad_perm:[1,0,3,2] row_mask:0xf bank_mask:0xf bound_ctrl:1
	v_add_f32_dpp v3, v3, v3 quad_perm:[1,0,3,2] row_mask:0xf bank_mask:0xf bound_ctrl:1
	s_nop 0
	v_add_f32_dpp v2, v2, v2 quad_perm:[2,3,0,1] row_mask:0xf bank_mask:0xf bound_ctrl:1
	v_add_f32_dpp v3, v3, v3 quad_perm:[2,3,0,1] row_mask:0xf bank_mask:0xf bound_ctrl:1
	s_nop 0
	v_add_f32_dpp v2, v2, v2 row_half_mirror row_mask:0xf bank_mask:0xf bound_ctrl:1
	v_add_f32_dpp v3, v3, v3 row_half_mirror row_mask:0xf bank_mask:0xf bound_ctrl:1
	s_nop 0
	v_add_f32_dpp v2, v2, v2 row_mirror row_mask:0xf bank_mask:0xf bound_ctrl:1
	v_add_f32_dpp v3, v3, v3 row_mirror row_mask:0xf bank_mask:0xf bound_ctrl:1
	s_and_saveexec_b64 s[0:1], vcc
	ds_write_b64 v96, v[2:3] offset:1024
	s_or_b64 exec, exec, s[0:1]
	s_waitcnt lgkmcnt(3)
	v_pk_mul_f32 v[2:3], v[36:37], v[40:41]
	v_pk_mul_f32 v[4:5], v[36:37], v[52:53]
	v_pk_fma_f32 v[2:3], v[34:35], v[38:39], v[2:3]
	v_pk_fma_f32 v[4:5], v[34:35], v[68:69], v[4:5]
	v_add_f32_e32 v2, v2, v3
	v_add_f32_e32 v3, v4, v5
	ds_read_b128 v[18:21], v97 offset:9472
	ds_read_b128 v[42:45], v97 offset:13568
	ds_read_b128 v[46:49], v97 offset:17664
	ds_read_b64 v[66:67], v98 offset:1280
	ds_read_b128 v[22:25], v97 offset:5376
	ds_read_b128 v[10:13], v97 offset:1280
	v_add_f32_dpp v2, v2, v2 quad_perm:[1,0,3,2] row_mask:0xf bank_mask:0xf bound_ctrl:1
	v_add_f32_dpp v3, v3, v3 quad_perm:[1,0,3,2] row_mask:0xf bank_mask:0xf bound_ctrl:1
	s_nop 0
	v_add_f32_dpp v2, v2, v2 quad_perm:[2,3,0,1] row_mask:0xf bank_mask:0xf bound_ctrl:1
	v_add_f32_dpp v3, v3, v3 quad_perm:[2,3,0,1] row_mask:0xf bank_mask:0xf bound_ctrl:1
	s_nop 0
	v_add_f32_dpp v2, v2, v2 row_half_mirror row_mask:0xf bank_mask:0xf bound_ctrl:1
	v_add_f32_dpp v3, v3, v3 row_half_mirror row_mask:0xf bank_mask:0xf bound_ctrl:1
	s_nop 0
	v_add_f32_dpp v2, v2, v2 row_mirror row_mask:0xf bank_mask:0xf bound_ctrl:1
	v_add_f32_dpp v4, v3, v3 row_mirror row_mask:0xf bank_mask:0xf bound_ctrl:1
	v_pk_mul_f32 v[34:35], v[30:31], v[2:3] op_sel_hi:[1,0]
	v_pk_mul_f32 v[2:3], v[32:33], v[2:3] op_sel_hi:[1,0]
	s_waitcnt lgkmcnt(8)
; #define LAS __attribute__((address_space(3)))
; template <int pass>
; __device__ __forceinline__ void rw_item(const Params& p, int l, int seg, int h, LAS float* sm, int tid, int lane, int wave) {
;     ...
;             const f32x4 w4 = nw4, k4 = nk4, a4 = na4, b4 = nb4, q4 = nq4; const f32x2 vv = nvv;
;             {
;                 const int tn = (t + 1 < TS) ? t + 1 : t, on = tn * 64 + kq * 4;
;                 nw4 = *(const LAS f32x4*)(bf + 1024 + on); nk4 = *(const LAS f32x4*)(bf + 2048 + on);
;                 na4 = *(const LAS f32x4*)(bf + 3072 + on); nb4 = *(const LAS f32x4*)(bf + 4096 + on);
;                 nvv = *(const LAS f32x2*)(bf + 5120 + tn * 64 + j0);
;                 if (pass == 1) nq4 = *(const LAS f32x4*)(bf + on);
;             }
;             const f32x2 vA = {vv.x, vv.x}, vB = {vv.y, vv.y};
;             f32x2 ua = b4.xy * sA[0], ub = b4.xy * sB[0];
;             ua = b4.zw * sA[1] + ua; ub = b4.zw * sB[1] + ub;
;             float uA = ua.x + ua.y, uB = ub.x + ub.y, gA = 0.f, gB = 0.f;
;             if (pass == 0) {
;                 f32x2 qa = b4.xy * pA[0], qb = b4.xy * pB[0];
;                 qa = b4.zw * pA[1] + qa; qb = b4.zw * pB[1] + qb;
;                 gA = qa.x + qa.y; gB = qb.x + qb.y;
;                 kq_sum16x4(uA, uB, gA, gB);
;             } else { uA = kq_sum<16>(uA); uB = kq_sum<16>(uB); }
;             const f32x2 uA2 = {uA, uA}, uB2 = {uB, uB};
;             { const f32x2 t0_ = k4.xy * vA - a4.xy * uA2, t1_ = k4.zw * vA - a4.zw * uA2; sA[0] = w4.xy * sA[0] + t0_; sA[1] = w4.zw * sA[1] + t1_; }
;             { const f32x2 t0_ = k4.xy * vB - a4.xy * uB2, t1_ = k4.zw * vB - a4.zw * uB2; sB[0] = w4.xy * sB[0] + t0_; sB[1] = w4.zw * sB[1] + t1_; }
;             if (pass == 0) {
;                 const f32x2 gA2 = {gA, gA}, gB2 = {gB, gB};
;                 pA[0] = w4.xy * pA[0] - a4.xy * gA2; pA[1] = w4.zw * pA[1] - a4.zw * gA2;
;                 pB[0] = w4.xy * pB[0] - a4.xy * gB2; pB[1] = w4.zw * pB[1] - a4.zw * gB2;
;             } else {
;                 f32x2 oa = q4.xy * sA[0], ob2 = q4.xy * sB[0];
;                 oa = q4.zw * sA[1] + oa; ob2 = q4.zw * sB[1] + ob2;
;                 const float oA = kq_sum<16>(oa.x + oa.y), oB = kq_sum<16>(ob2.x + ob2.y);
;                 if (kq == 0) *(LAS f32x2*)(ob + t * 64 + j0) = (f32x2){oA, oB};
	v_pk_fma_f32 v[34:35], v[14:15], v[50:51], v[34:35] op_sel_hi:[1,0,1] neg_lo:[0,0,1] neg_hi:[0,0,1]
	v_pk_fma_f32 v[2:3], v[16:17], v[50:51], v[2:3] op_sel_hi:[1,0,1] neg_lo:[0,0,1] neg_hi:[0,0,1]
	s_waitcnt lgkmcnt(7)
	v_pk_fma_f32 v[70:71], v[26:27], v[38:39], v[34:35]
	v_pk_fma_f32 v[72:73], v[28:29], v[40:41], v[2:3]
	v_pk_mul_f32 v[2:3], v[30:31], v[4:5] op_sel_hi:[1,0]
	v_pk_mul_f32 v[4:5], v[32:33], v[4:5] op_sel_hi:[1,0]
	v_pk_fma_f32 v[2:3], v[14:15], v[50:51], v[2:3] op_sel:[0,1,0] neg_lo:[0,0,1] neg_hi:[0,0,1]
	v_pk_fma_f32 v[4:5], v[16:17], v[50:51], v[4:5] op_sel:[0,1,0] neg_lo:[0,0,1] neg_hi:[0,0,1]
	v_pk_fma_f32 v[14:15], v[26:27], v[68:69], v[2:3]
	v_pk_fma_f32 v[16:17], v[28:29], v[52:53], v[4:5]
	s_waitcnt lgkmcnt(6)
	v_pk_mul_f32 v[2:3], v[6:7], v[70:71]
	v_pk_mul_f32 v[4:5], v[6:7], v[14:15]
	v_pk_fma_f32 v[2:3], v[8:9], v[72:73], v[2:3]
	v_pk_fma_f32 v[4:5], v[8:9], v[16:17], v[4:5]
	v_add_f32_e32 v2, v2, v3
	v_add_f32_e32 v3, v4, v5
	s_nop 1
	v_add_f32_dpp v2, v2, v2 quad_perm:[1,0,3,2] row_mask:0xf bank_mask:0xf bound_ctrl:1
	v_add_f32_dpp v3, v3, v3 quad_perm:[1,0,3,2] row_mask:0xf bank_mask:0xf bound_ctrl:1
	s_nop 0
	v_add_f32_dpp v2, v2, v2 quad_perm:[2,3,0,1] row_mask:0xf bank_mask:0xf bound_ctrl:1
	v_add_f32_dpp v3, v3, v3 quad_perm:[2,3,0,1] row_mask:0xf bank_mask:0xf bound_ctrl:1
	s_nop 0
	v_add_f32_dpp v2, v2, v2 row_half_mirror row_mask:0xf bank_mask:0xf bound_ctrl:1
	v_add_f32_dpp v3, v3, v3 row_half_mirror row_mask:0xf bank_mask:0xf bound_ctrl:1
	s_nop 0
	v_add_f32_dpp v2, v2, v2 row_mirror row_mask:0xf bank_mask:0xf bound_ctrl:1
	v_add_f32_dpp v3, v3, v3 row_mirror row_mask:0xf bank_mask:0xf bound_ctrl:1
	s_and_saveexec_b64 s[0:1], vcc
	ds_write_b64 v96, v[2:3] offset:1280
	s_or_b64 exec, exec, s[0:1]
	s_waitcnt lgkmcnt(3)
	v_pk_mul_f32 v[26:27], v[48:49], v[72:73]
	v_pk_mul_f32 v[28:29], v[48:49], v[16:17]
	v_pk_fma_f32 v[26:27], v[46:47], v[70:71], v[26:27]
	v_pk_fma_f32 v[28:29], v[46:47], v[14:15], v[28:29]
	v_add_f32_e32 v26, v26, v27
	v_add_f32_e32 v27, v28, v29
	ds_read_b128 v[2:5], v97 offset:9728
	ds_read_b128 v[38:41], v97 offset:13824
	ds_read_b128 v[6:9], v97 offset:17920
	ds_read_b64 v[52:53], v98 offset:1536
	ds_read_b128 v[34:37], v97 offset:5632
	ds_read_b128 v[30:33], v97 offset:1536
	v_add_f32_dpp v26, v26, v26 quad_perm:[1,0,3,2] row_mask:0xf bank_mask:0xf bound_ctrl:1
	v_add_f32_dpp v27, v27, v27 quad_perm:[1,0,3,2] row_mask:0xf bank_mask:0xf bound_ctrl:1
	s_nop 0
	v_add_f32_dpp v26, v26, v26 quad_perm:[2,3,0,1] row_mask:0xf bank_mask:0xf bound_ctrl:1
	v_add_f32_dpp v27, v27, v27 quad_perm:[2,3,0,1] row_mask:0xf bank_mask:0xf bound_ctrl:1
	s_nop 0
	v_add_f32_dpp v26, v26, v26 row_half_mirror row_mask:0xf bank_mask:0xf bound_ctrl:1
	v_add_f32_dpp v27, v27, v27 row_half_mirror row_mask:0xf bank_mask:0xf bound_ctrl:1
	s_nop 0
	v_add_f32_dpp v26, v26, v26 row_mirror row_mask:0xf bank_mask:0xf bound_ctrl:1
	v_add_f32_dpp v28, v27, v27 row_mirror row_mask:0xf bank_mask:0xf bound_ctrl:1
	v_pk_mul_f32 v[46:47], v[42:43], v[26:27] op_sel_hi:[1,0]
	v_pk_mul_f32 v[26:27], v[44:45], v[26:27] op_sel_hi:[1,0]
	s_waitcnt lgkmcnt(8)
	v_pk_fma_f32 v[46:47], v[18:19], v[66:67], v[46:47] op_sel_hi:[1,0,1] neg_lo:[0,0,1] neg_hi:[0,0,1]
	v_pk_fma_f32 v[26:27], v[20:21], v[66:67], v[26:27] op_sel_hi:[1,0,1] neg_lo:[0,0,1] neg_hi:[0,0,1]
	s_waitcnt lgkmcnt(7)
	v_pk_fma_f32 v[46:47], v[22:23], v[70:71], v[46:47]
	v_pk_fma_f32 v[48:49], v[24:25], v[72:73], v[26:27]
	v_pk_mul_f32 v[26:27], v[42:43], v[28:29] op_sel_hi:[1,0]
	s_nop 0
	v_pk_fma_f32 v[18:19], v[18:19], v[66:67], v[26:27] op_sel:[0,1,0] neg_lo:[0,0,1] neg_hi:[0,0,1]
	v_pk_mul_f32 v[26:27], v[44:45], v[28:29] op_sel_hi:[1,0]
	v_pk_fma_f32 v[42:43], v[22:23], v[14:15], v[18:19]
	v_pk_fma_f32 v[20:21], v[20:21], v[66:67], v[26:27] op_sel:[0,1,0] neg_lo:[0,0,1] neg_hi:[0,0,1]
	s_waitcnt lgkmcnt(6)
; #define LAS __attribute__((address_space(3)))
; template <int pass>
; __device__ __forceinline__ void rw_item(const Params& p, int l, int seg, int h, LAS float* sm, int tid, int lane, int wave) {
;     ...
;             const f32x4 w4 = nw4, k4 = nk4, a4 = na4, b4 = nb4, q4 = nq4; const f32x2 vv = nvv;
;             {
;                 const int tn = (t + 1 < TS) ? t + 1 : t, on = tn * 64 + kq * 4;
;                 nw4 = *(const LAS f32x4*)(bf + 1024 + on); nk4 = *(const LAS f32x4*)(bf + 2048 + on);
;                 na4 = *(const LAS f32x4*)(bf + 3072 + on); nb4 = *(const LAS f32x4*)(bf + 4096 + on);
;                 nvv = *(const LAS f32x2*)(bf + 5120 + tn * 64 + j0);
;                 if (pass == 1) nq4 = *(const LAS f32x4*)(bf + on);
;             }
;             const f32x2 vA = {vv.x, vv.x}, vB = {vv.y, vv.y};
;             f32x2 ua = b4.xy * sA[0], ub = b4.xy * sB[0];
;             ua = b4.zw * sA[1] + ua; ub = b4.zw * sB[1] + ub;
;             float uA = ua.x + ua.y, uB = ub.x + ub.y, gA = 0.f, gB = 0.f;
;             if (pass == 0) {
;                 f32x2 qa = b4.xy * pA[0], qb = b4.xy * pB[0];
;                 qa = b4.zw * pA[1] + qa; qb = b4.zw * pB[1] + qb;
;                 gA = qa.x + qa.y; gB = qb.x + qb.y;
;                 kq_sum16x4(uA, uB, gA, gB);
;             } else { uA = kq_sum<16>(uA); uB = kq_sum<16>(uB); }
;             const f32x2 uA2 = {uA, uA}, uB2 = {uB, uB};
;             { const f32x2 t0_ = k4.xy * vA - a4.xy * uA2, t1_ = k4.zw * vA - a4.zw * uA2; sA[0] = w4.xy * sA[0] + t0_; sA[1] = w4.zw * sA[1] + t1_; }
;             { const f32x2 t0_ = k4.xy * vB - a4.xy * uB2, t1_ = k4.zw * vB - a4.zw * uB2; sB[0] = w4.xy * sB[0] + t0_; sB[1] = w4.zw * sB[1] + t1_; }
;             if (pass == 0) {
;                 const f32x2 gA2 = {gA, gA}, gB2 = {gB, gB};
;                 pA[0] = w4.xy * pA[0] - a4.xy * gA2; pA[1] = w4.zw * pA[1] - a4.zw * gA2;
;                 pB[0] = w4.xy * pB[0] - a4.xy * gB2; pB[1] = w4.zw * pB[1] - a4.zw * gB2;
;             } else {
;                 f32x2 oa = q4.xy * sA[0], ob2 = q4.xy * sB[0];
;                 oa = q4.zw * sA[1] + oa; ob2 = q4.zw * sB[1] + ob2;
;                 const float oA = kq_sum<16>(oa.x + oa.y), oB = kq_sum<16>(ob2.x + ob2.y);
;                 if (kq == 0) *(LAS f32x2*)(ob + t * 64 + j0) = (f32x2){oA, oB};
;             }
	v_pk_mul_f32 v[14:15], v[10:11], v[46:47]
	v_pk_fma_f32 v[44:45], v[24:25], v[16:17], v[20:21]
	v_pk_mul_f32 v[10:11], v[10:11], v[42:43]
	v_pk_fma_f32 v[14:15], v[12:13], v[48:49], v[14:15]
	v_pk_fma_f32 v[10:11], v[12:13], v[44:45], v[10:11]
	v_add_f32_e32 v11, v10, v11
	v_add_f32_e32 v10, v14, v15
	s_nop 1
	v_add_f32_dpp v10, v10, v10 quad_perm:[1,0,3,2] row_mask:0xf bank_mask:0xf bound_ctrl:1
	v_add_f32_dpp v11, v11, v11 quad_perm:[1,0,3,2] row_mask:0xf bank_mask:0xf bound_ctrl:1
	s_nop 0
	v_add_f32_dpp v10, v10, v10 quad_perm:[2,3,0,1] row_mask:0xf bank_mask:0xf bound_ctrl:1
	v_add_f32_dpp v11, v11, v11 quad_perm:[2,3,0,1] row_mask:0xf bank_mask:0xf bound_ctrl:1
	s_nop 0
	v_add_f32_dpp v10, v10, v10 row_half_mirror row_mask:0xf bank_mask:0xf bound_ctrl:1
	v_add_f32_dpp v11, v11, v11 row_half_mirror row_mask:0xf bank_mask:0xf bound_ctrl:1
	s_nop 0
	v_add_f32_dpp v10, v10, v10 row_mirror row_mask:0xf bank_mask:0xf bound_ctrl:1
	v_add_f32_dpp v11, v11, v11 row_mirror row_mask:0xf bank_mask:0xf bound_ctrl:1
	s_and_saveexec_b64 s[0:1], vcc
	ds_write_b64 v96, v[10:11] offset:1536
	s_or_b64 exec, exec, s[0:1]
	s_waitcnt lgkmcnt(3)
	v_pk_mul_f32 v[66:67], v[8:9], v[48:49]
	v_pk_mul_f32 v[8:9], v[8:9], v[44:45]
	v_pk_fma_f32 v[66:67], v[6:7], v[46:47], v[66:67]
	v_pk_fma_f32 v[6:7], v[6:7], v[42:43], v[8:9]
	v_add_f32_e32 v8, v66, v67
	v_add_f32_e32 v7, v6, v7
	s_cmpk_lg_i32 s38, 0x800
	v_add_f32_dpp v6, v8, v8 quad_perm:[1,0,3,2] row_mask:0xf bank_mask:0xf bound_ctrl:1
	v_add_f32_dpp v7, v7, v7 quad_perm:[1,0,3,2] row_mask:0xf bank_mask:0xf bound_ctrl:1
	s_cselect_b32 s0, s37, 0x3c0
	v_add_f32_dpp v6, v6, v6 quad_perm:[2,3,0,1] row_mask:0xf bank_mask:0xf bound_ctrl:1
	v_add_f32_dpp v7, v7, v7 quad_perm:[2,3,0,1] row_mask:0xf bank_mask:0xf bound_ctrl:1
	v_or_b32_e32 v10, s0, v0
	v_add_f32_dpp v6, v6, v6 row_half_mirror row_mask:0xf bank_mask:0xf bound_ctrl:1
	v_add_f32_dpp v7, v7, v7 row_half_mirror row_mask:0xf bank_mask:0xf bound_ctrl:1
	v_lshl_add_u32 v22, v10, 2, s5
	v_add_f32_dpp v6, v6, v6 row_mirror row_mask:0xf bank_mask:0xf bound_ctrl:1
	v_add_f32_dpp v66, v7, v7 row_mirror row_mask:0xf bank_mask:0xf bound_ctrl:1
	v_pk_mul_f32 v[8:9], v[38:39], v[6:7] op_sel_hi:[1,0]
	v_pk_mul_f32 v[38:39], v[38:39], v[66:67] op_sel_hi:[1,0]
	s_waitcnt lgkmcnt(2)
	v_pk_fma_f32 v[8:9], v[2:3], v[52:53], v[8:9] op_sel_hi:[1,0,1] neg_lo:[0,0,1] neg_hi:[0,0,1]
	v_pk_mul_f32 v[6:7], v[40:41], v[6:7] op_sel_hi:[1,0]
	v_pk_fma_f32 v[2:3], v[2:3], v[52:53], v[38:39] op_sel:[0,1,0] neg_lo:[0,0,1] neg_hi:[0,0,1]
	v_pk_mul_f32 v[38:39], v[40:41], v[66:67] op_sel_hi:[1,0]
	v_pk_fma_f32 v[68:69], v[4:5], v[52:53], v[6:7] op_sel_hi:[1,0,1] neg_lo:[0,0,1] neg_hi:[0,0,1]
	s_waitcnt lgkmcnt(1)
	v_pk_fma_f32 v[6:7], v[34:35], v[46:47], v[8:9]
	v_pk_fma_f32 v[4:5], v[4:5], v[52:53], v[38:39] op_sel:[0,1,0] neg_lo:[0,0,1] neg_hi:[0,0,1]
	v_pk_fma_f32 v[2:3], v[34:35], v[42:43], v[2:3]
	v_pk_fma_f32 v[8:9], v[36:37], v[48:49], v[68:69]
	v_pk_fma_f32 v[4:5], v[36:37], v[44:45], v[4:5]
	s_waitcnt lgkmcnt(0)
	v_pk_mul_f32 v[34:35], v[30:31], v[6:7]
	v_pk_mul_f32 v[30:31], v[30:31], v[2:3]
	v_pk_fma_f32 v[34:35], v[32:33], v[8:9], v[34:35]
	v_pk_fma_f32 v[30:31], v[32:33], v[4:5], v[30:31]
	v_add_f32_e32 v31, v30, v31
	v_add_f32_e32 v30, v34, v35
	v_lshl_add_u32 v10, s0, 2, v93
	ds_read_b128 v[14:17], v22 offset:8192
	ds_read_b128 v[18:21], v22 offset:12288
	ds_read_b128 v[26:29], v22 offset:16384
	ds_read_b64 v[50:51], v10 offset:20480
	ds_read_b128 v[10:13], v22 offset:4096
	ds_read_b128 v[22:25], v22
	v_add_f32_dpp v30, v30, v30 quad_perm:[1,0,3,2] row_mask:0xf bank_mask:0xf bound_ctrl:1
	v_add_f32_dpp v31, v31, v31 quad_perm:[1,0,3,2] row_mask:0xf bank_mask:0xf bound_ctrl:1
	s_nop 0
	v_add_f32_dpp v30, v30, v30 quad_perm:[2,3,0,1] row_mask:0xf bank_mask:0xf bound_ctrl:1
	v_add_f32_dpp v31, v31, v31 quad_perm:[2,3,0,1] row_mask:0xf bank_mask:0xf bound_ctrl:1
	s_nop 0
	v_add_f32_dpp v30, v30, v30 row_half_mirror row_mask:0xf bank_mask:0xf bound_ctrl:1
	v_add_f32_dpp v31, v31, v31 row_half_mirror row_mask:0xf bank_mask:0xf bound_ctrl:1
	s_nop 0
	v_add_f32_dpp v30, v30, v30 row_mirror row_mask:0xf bank_mask:0xf bound_ctrl:1
	v_add_f32_dpp v31, v31, v31 row_mirror row_mask:0xf bank_mask:0xf bound_ctrl:1
	s_and_saveexec_b64 s[0:1], vcc
	s_cbranch_execz .LBB0_456
	ds_write_b64 v96, v[30:31] offset:1792
	s_branch .LBB0_456

; #define LAS __attribute__((address_space(3)))
;     __device__ __forceinline__ unsigned char* ws() const { return (unsigned char*)(__attribute__((address_space(1))) unsigned char*)ld(35); }
; __device__ __forceinline__ void phase_combine(const Params& p, LAS unsigned char* lds, int tid, int lane, int wave, bool dummy) {
;     ...
;     for (int b = blockIdx.x; b < 124; b += gridDim.x) {
;         if (b < 24) {
;             const int head = b >> 2, nt = b & 3, row = lane & 15, q = lane >> 4;
;             float* Lm = (float*)(ws + WS_RWL); const float* Pm = (const float*)(ws + WS_RWP);
;             LAS float* buf = (LAS float*)lds;
;             LAS float* sbuf = buf + 8192;
;             constexpr size_t SS = 6 * 4096;
;             const float* pbase = Pm + (size_t)head * 4096 + tid * 8;
;             const int wv = wave & 3;
;             float* lbase = Lm + ((size_t)head * 64 + 16 * nt + row) * 64 + 16 * wv + 4 * q;
;             float* sbase = (dummy ? (float*)(ws + WS_H) : Lm) + ((size_t)head * 64 + 16 * nt + row) * 64 + 16 * wv + 4 * q;
;     ...
;             int e = (b - 24) * 512 + tid;
.LBB0_478:
	s_andn2_b64 vcc, exec, s[0:1]
	s_cbranch_vccnz .LBB0_514
	v_readlane_b32 s0, v253, 35
	s_nop 1
	v_mov_b32_e32 v0, s0
	ds_read_b64 v[2:3], v0
	v_readlane_b32 s0, v253, 5
	v_readlane_b32 s1, v253, 6
	s_andn2_b64 vcc, exec, s[0:1]
	s_waitcnt lgkmcnt(0)
	v_readfirstlane_b32 s0, v2
	v_readfirstlane_b32 s1, v3
	s_cbranch_vccnz .LBB0_514
	v_lshlrev_b32_e32 v2, 3, v78
	v_ashrrev_i32_e32 v3, 31, v2
	s_add_u32 s2, s0, 0xef80000
	v_lshl_add_u64 v[2:3], v[2:3], 2, s[0:1]
	s_mov_b64 s[4:5], 0xfb80000
	v_readlane_b32 s8, v254, 57
	s_addc_u32 s7, s1, 0
	v_lshl_add_u64 v[82:83], v[2:3], 0, s[4:5]
	s_lshl_b32 s4, s8, 4
	s_and_b32 s6, s4, 48
	s_lshl_b32 s10, s6, 2
	s_add_u32 s4, s2, s10
	s_addc_u32 s5, s7, 0
	v_and_b32_e32 v0, 48, v174
	v_lshl_add_u64 v[84:85], s[4:5], 0, v[0:1]
	v_lshlrev_b32_e32 v0, 4, v174
	s_cmp_lt_i32 s8, 4
	v_and_b32_e32 v4, 0x300, v0
	s_cselect_b64 s[8:9], -1, 0
	v_lshl_or_b32 v6, s6, 6, v4
	s_add_i32 s6, 0, 0x8000
	s_waitcnt vmcnt(0)
	v_and_b32_e32 v80, 15, v78
	s_add_i32 s10, s10, 0
	s_waitcnt vmcnt(0)
	v_lshl_add_u32 v180, v78, 2, s6
	s_and_b32 s6, s44, 0xc0
	v_lshlrev_b32_e32 v2, 2, v80
	v_and_b32_e32 v0, 48, v78
	s_add_u32 s6, s2, s6
	s_movk_i32 s4, 0x800
	v_add_u32_e32 v3, 0, v2
	v_lshlrev_b32_e32 v5, 2, v0
	s_addc_u32 s7, s7, 0
	v_and_b32_e32 v79, 0xff, v78
	v_add_u32_e32 v79, 0xffffe800, v79
	v_lshl_add_u32 v81, v78, 5, 0
	v_cmp_gt_i32_e64 s[4:5], s4, v78
	v_add3_u32 v175, s10, v2, v4
	v_add_u32_e32 v176, v3, v5
	v_add3_u32 v177, s10, v4, v2
	v_add3_u32 v178, 0, v5, v2
	v_add_u32_e32 v179, v3, v6
	v_add_u32_e32 v181, 0xfffffe00, v78
	v_lshl_add_u64 v[86:87], s[6:7], 0, v[0:1]
	v_readlane_b32 s14, v253, 33
	s_mov_b32 s15, s58
	s_branch .LBB0_483

; __device__ __forceinline__ void phase_combine(const Params& p, LAS unsigned char* lds, int tid, int lane, int wave, bool dummy) {
;     ...
;     for (int b = blockIdx.x; b < 124; b += gridDim.x) {
.LBB0_482:
	s_add_i32 s15, s15, s76
	s_add_i32 s14, s14, s43
	s_cmpk_gt_i32 s15, 0xdf
	s_cbranch_scc1 .LBB0_514

;     __device__ __forceinline__ unsigned char* ws() const { return (unsigned char*)(__attribute__((address_space(1))) unsigned char*)ld(35); }
; __device__ __forceinline__ void phase_combine(const Params& p, LAS unsigned char* lds, int tid, int lane, int wave, bool dummy) {
;     ...
;             int e = (b - 24) * 512 + tid;
;             float* Lm; const float* Dm; size_t lstride, dstride; size_t lo, dof;
;             if (e < 4 * 8192) { const int h = e / 8192, rem = e % 8192, c = rem % 128; Lm = (float*)(ws + WS_HGL); Dm = (const float*)(ws + WS_HGD); lstride = 4 * 8192; dstride = 4 * 128; lo = (size_t)h * 8192 + rem; dof = (size_t)h * 128 + c; }
;             else { e -= 4 * 8192; const int h = e / 4608, rem = e % 4608, c = rem % 48; Lm = (float*)(ws + WS_GLL); Dm = (const float*)(ws + WS_GLD); lstride = 4 * 4608; dstride = 4 * 48; lo = (size_t)h * 4608 + rem; dof = (size_t)h * 48 + c; }
.LBB0_485:
	s_cmpk_gt_u32 s44, 0xff
	s_cbranch_scc1 .LBB0_482
	v_lshl_add_u32 v0, s15, 8, v79
	s_mov_b32 s2, 0x8000
	v_cmp_gt_i32_e32 vcc, s2, v0
	s_and_saveexec_b64 s[6:7], vcc
	s_xor_b64 s[6:7], exec, s[6:7]
	s_cbranch_execz .LBB0_487
	v_ashrrev_i32_e32 v2, 31, v0
	v_lshrrev_b32_e32 v2, 19, v2
	v_add_u32_e32 v2, v0, v2
	v_ashrrev_i32_e32 v2, 13, v2
	v_mul_i32_i24_e32 v3, 0x2000, v2
	v_sub_u32_e32 v4, v0, v3
	v_ashrrev_i16_e32 v0, 15, v4
	v_lshrrev_b16_e32 v0, 9, v0
	v_add_u16_e32 v0, v4, v0
	v_and_b32_e32 v0, 0xffffff80, v0
	v_ashrrev_i32_e32 v3, 31, v2
	v_sub_u16_e32 v0, v4, v0
	v_lshlrev_b64 v[6:7], 13, v[2:3]
	v_ashrrev_i32_e32 v5, 31, v4
	v_lshl_add_u64 v[6:7], v[6:7], 0, v[4:5]
	v_bfe_i32 v4, v0, 0, 16
	v_lshlrev_b64 v[2:3], 7, v[2:3]
	v_ashrrev_i32_e32 v5, 31, v4
	v_lshl_add_u64 v[8:9], v[2:3], 0, v[4:5]
